# LRU: dir-0 gate-weight fragment loads issued after the conv-stage vmcnt(0) (hidden behind conv compute) instead of behind the barrier
# baseline (speedup 1.0000x reference)
; DI unsigned cvtpk(float lo, float hi) { unsigned r; asm volatile("v_cvt_pk_bf16_f32 %0, %1, %2" : "=v"(r) : "v"(lo), "v"(hi)); return r; }
; DI void lru_tile(const Params& p, unsigned char* shm, int c, int nb, const LruPar par) {
;     ...
;         for (int o = 0; o < 4; ++o) { float u8[8];
; #pragma unroll
;             for (int i = 0; i < 8; ++i) { float a = bias[i];
; #pragma unroll
;                 for (int tp = 0; tp < 4; ++tp) a += xr[o + tp][i] * w[tp][i];
;                 u8[i] = a; }
;             *(u32x4*)(UB + (rg * 4 + o) * LDU + cgp * 8) = (u32x4){cvtpk(u8[0], u8[1]), cvtpk(u8[2], u8[3]), cvtpk(u8[4], u8[5]), cvtpk(u8[6], u8[7])};
;         }
;     ...
;         for (int s = 0; s < 4; ++s)
; #pragma unroll
;             for (int gt = 0; gt < 2; ++gt) bfr[s][gt] = *(const bf16x8*)(LWT + ((size_t)((d * 2 + gt) * 16 + nb) * 128 + chl) * 128 + s * 32 + q * 8);
.LBB0_228:
	s_or_b64 exec, exec, s[4:5]
	s_waitcnt vmcnt(0)
	v_and_b32_e32 v240, 0x3c0, v202
	v_lshrrev_b32_e32 v240, 2, v240
	v_and_or_b32 v240, v202, 15, v240
	v_add_u32_e32 v240, s38, v240
	v_bfe_u32 v241, v202, 4, 2
	v_lshlrev_b32_e32 v240, 8, v240
	v_lshl_add_u32 v240, v241, 4, v240
	s_add_u32 s72, s34, 0x80000
	s_addc_u32 s73, s35, 0
	global_load_dwordx4 v[208:211], v240, s[34:35]
	global_load_dwordx4 v[216:219], v240, s[34:35] offset:64
	global_load_dwordx4 v[212:215], v240, s[72:73]
	global_load_dwordx4 v[220:223], v240, s[72:73] offset:64
	global_load_dwordx4 v[224:227], v240, s[34:35] offset:128
	global_load_dwordx4 v[232:235], v240, s[34:35] offset:192
	global_load_dwordx4 v[228:231], v240, s[72:73] offset:128
	global_load_dwordx4 v[236:239], v240, s[72:73] offset:192
	v_lshlrev_b32_e32 v109, 16, v61
	v_and_b32_e32 v105, 0xffff0000, v61
	v_lshlrev_b32_e32 v97, 16, v63
	v_and_b32_e32 v61, 0xffff0000, v63
	v_lshlrev_b32_e32 v115, 16, v57
	v_and_b32_e32 v111, 0xffff0000, v57
	v_lshlrev_b32_e32 v107, 16, v58
	v_and_b32_e32 v103, 0xffff0000, v58
	v_lshlrev_b32_e32 v63, 16, v59
	v_and_b32_e32 v57, 0xffff0000, v59
	v_lshlrev_b32_e32 v133, 16, v53
	v_and_b32_e32 v131, 0xffff0000, v53
	v_lshlrev_b32_e32 v125, 16, v55
	v_and_b32_e32 v59, 0xffff0000, v55
	v_lshlrev_b32_e32 v124, 16, v51
	v_and_b32_e32 v58, 0xffff0000, v51
	v_lshlrev_b32_e32 v139, 16, v44
	v_lshlrev_b32_e32 v138, 16, v40
	v_lshlrev_b32_e32 v123, 16, v64
	v_and_b32_e32 v55, 0xffff0000, v64
	v_lshlrev_b32_e32 v53, 16, v65
	v_and_b32_e32 v51, 0xffff0000, v65
	v_mov_b32_e32 v64, v36
	v_mov_b32_e32 v65, v12
	v_lshlrev_b32_e32 v132, 16, v49
	v_and_b32_e32 v130, 0xffff0000, v49
	v_lshlrev_b32_e32 v143, 16, v45
	v_and_b32_e32 v145, 0xffff0000, v45
	v_lshlrev_b32_e32 v151, 16, v47
	v_and_b32_e32 v153, 0xffff0000, v47
	v_lshlrev_b32_e32 v150, 16, v43
	v_and_b32_e32 v152, 0xffff0000, v43
	v_lshlrev_b32_e32 v49, 16, v66
	v_and_b32_e32 v47, 0xffff0000, v66
	v_lshlrev_b32_e32 v45, 16, v67
	v_and_b32_e32 v43, 0xffff0000, v67
	v_pk_mul_f32 v[66:67], v[64:65], v[138:139]
	v_lshlrev_b32_e32 v137, 16, v52
	v_add_f32_e32 v12, v20, v66
	v_lshlrev_b32_e32 v136, 16, v48
	v_add_f32_e32 v12, v12, v67
	v_mov_b32_e32 v66, v32
	v_mov_b32_e32 v67, v16
	v_pk_mul_f32 v[154:155], v[66:67], v[136:137]
	v_and_b32_e32 v141, 0xffff0000, v44
	v_add_f32_e32 v12, v12, v154
	v_and_b32_e32 v140, 0xffff0000, v40
	v_lshlrev_b32_e32 v142, 16, v41
	v_and_b32_e32 v144, 0xffff0000, v41
	v_add_f32_e32 v41, v12, v155
	v_mov_b32_e32 v12, v37
	v_pk_mul_f32 v[36:37], v[12:13], v[140:141]
	v_and_b32_e32 v135, 0xffff0000, v52
	v_add_f32_e32 v16, v21, v36
	v_and_b32_e32 v134, 0xffff0000, v48
	v_add_f32_e32 v36, v16, v37
	v_mov_b32_e32 v16, v33
	v_pk_mul_f32 v[32:33], v[16:17], v[134:135]
	v_lshlrev_b32_e32 v146, 16, v42
	v_add_f32_e32 v32, v36, v32
	v_and_b32_e32 v148, 0xffff0000, v42
	v_add_f32_e32 v42, v32, v33
	v_mov_b32_e32 v32, v38
	v_mov_b32_e32 v33, v14
	v_pk_mul_f32 v[36:37], v[32:33], v[142:143]
	v_lshlrev_b32_e32 v147, 16, v46
	v_add_f32_e32 v14, v22, v36
	v_add_f32_e32 v14, v14, v37
	v_mov_b32_e32 v36, v34
	v_mov_b32_e32 v37, v18
	v_pk_mul_f32 v[154:155], v[36:37], v[132:133]
	v_and_b32_e32 v149, 0xffff0000, v46
	v_add_f32_e32 v14, v14, v154
	v_add_f32_e32 v44, v14, v155
	v_mov_b32_e32 v14, v39
	v_pk_mul_f32 v[38:39], v[14:15], v[144:145]
	v_lshlrev_b32_e32 v129, 16, v54
	v_add_f32_e32 v18, v23, v38
	v_add_f32_e32 v38, v18, v39
	v_mov_b32_e32 v18, v35
	v_pk_mul_f32 v[34:35], v[18:19], v[130:131]
	v_lshlrev_b32_e32 v128, 16, v50
	v_add_f32_e32 v34, v38, v34
	v_add_f32_e32 v46, v34, v35
	v_mov_b32_e32 v34, v28
	v_mov_b32_e32 v35, v0
	v_pk_mul_f32 v[38:39], v[34:35], v[146:147]
	v_and_b32_e32 v127, 0xffff0000, v54
	v_add_f32_e32 v0, v8, v38
	v_add_f32_e32 v0, v0, v39
	v_mov_b32_e32 v38, v24
	v_mov_b32_e32 v39, v4
	v_pk_mul_f32 v[154:155], v[38:39], v[128:129]
	v_and_b32_e32 v126, 0xffff0000, v50
	v_add_f32_e32 v0, v0, v154
	v_add_f32_e32 v48, v0, v155
	v_mov_b32_e32 v0, v29
	v_pk_mul_f32 v[28:29], v[0:1], v[148:149]
	v_mov_b32_e32 v154, v26
	v_add_f32_e32 v4, v9, v28
	v_add_f32_e32 v28, v4, v29
	v_mov_b32_e32 v4, v25
	v_pk_mul_f32 v[24:25], v[4:5], v[126:127]
	v_mov_b32_e32 v29, v2
	v_add_f32_e32 v24, v28, v24
	v_mov_b32_e32 v28, v30
	v_add_f32_e32 v50, v24, v25
	v_pk_mul_f32 v[24:25], v[28:29], v[150:151]
	v_mov_b32_e32 v155, v6
	v_add_f32_e32 v2, v10, v24
	v_add_f32_e32 v2, v2, v25
	v_pk_mul_f32 v[24:25], v[154:155], v[124:125]
	v_lshl_add_u32 v40, v98, 1, 0
	v_add_f32_e32 v2, v2, v24
	v_add_f32_e32 v30, v2, v25
	v_mov_b32_e32 v2, v31
	v_pk_mul_f32 v[24:25], v[2:3], v[152:153]
	s_ashr_i32 s4, s6, 6
	v_add_f32_e32 v6, v11, v24
	v_add_f32_e32 v26, v6, v25
	v_mov_b32_e32 v6, v27
	v_pk_mul_f32 v[24:25], v[6:7], v[58:59]
	v_lshlrev_b32_e32 v121, 16, v56
	v_add_f32_e32 v24, v26, v24
	v_add_f32_e32 v27, v24, v25
	v_cvt_pk_bf16_f32 v24, v41, v42
	v_cvt_pk_bf16_f32 v25, v44, v46
	v_cvt_pk_bf16_f32 v26, v48, v50
	v_cvt_pk_bf16_f32 v27, v30, v27
	v_mad_u64_u32 v[30:31], s[6:7], v95, s67, v[40:41]
	ds_write_b128 v30, v[24:27]
	v_mov_b32_e32 v24, v139
	v_mov_b32_e32 v25, v136
	v_pk_mul_f32 v[24:25], v[64:65], v[24:25]
	v_mov_b32_e32 v120, v137
	v_add_f32_e32 v24, v20, v24
	v_add_f32_e32 v26, v24, v25
	v_pk_mul_f32 v[24:25], v[66:67], v[120:121]
	v_and_b32_e32 v119, 0xffff0000, v56
	v_add_f32_e32 v24, v26, v24
	v_add_f32_e32 v26, v24, v25
	v_mov_b32_e32 v24, v141
	v_mov_b32_e32 v25, v134
	v_pk_mul_f32 v[24:25], v[12:13], v[24:25]
	v_mov_b32_e32 v118, v135
	v_add_f32_e32 v24, v21, v24
	v_add_f32_e32 v27, v24, v25
	v_pk_mul_f32 v[24:25], v[16:17], v[118:119]
	v_mov_b32_e32 v114, v133
	v_add_f32_e32 v24, v27, v24
	v_add_f32_e32 v27, v24, v25
; DI unsigned cvtpk(float lo, float hi) { unsigned r; asm volatile("v_cvt_pk_bf16_f32 %0, %1, %2" : "=v"(r) : "v"(lo), "v"(hi)); return r; }
; DI void lru_tile(const Params& p, unsigned char* shm, int c, int nb, const LruPar par) {
;     ...
;         for (int o = 0; o < 4; ++o) { float u8[8];
; #pragma unroll
;             for (int i = 0; i < 8; ++i) { float a = bias[i];
; #pragma unroll
;                 for (int tp = 0; tp < 4; ++tp) a += xr[o + tp][i] * w[tp][i];
;                 u8[i] = a; }
;             *(u32x4*)(UB + (rg * 4 + o) * LDU + cgp * 8) = (u32x4){cvtpk(u8[0], u8[1]), cvtpk(u8[2], u8[3]), cvtpk(u8[4], u8[5]), cvtpk(u8[6], u8[7])};
;         }
;     }
;     __syncthreads();
	v_mov_b32_e32 v24, v143
	v_mov_b32_e32 v25, v132
	v_pk_mul_f32 v[24:25], v[32:33], v[24:25]
	v_mov_b32_e32 v110, v131
	v_add_f32_e32 v24, v22, v24
	v_add_f32_e32 v31, v24, v25
	v_pk_mul_f32 v[24:25], v[36:37], v[114:115]
	v_mov_b32_e32 v106, v129
	v_add_f32_e32 v24, v31, v24
	v_add_f32_e32 v31, v24, v25
	v_mov_b32_e32 v24, v145
	v_mov_b32_e32 v25, v130
	v_pk_mul_f32 v[24:25], v[14:15], v[24:25]
	v_mov_b32_e32 v102, v127
	v_add_f32_e32 v24, v23, v24
	v_add_f32_e32 v41, v24, v25
	v_pk_mul_f32 v[24:25], v[18:19], v[110:111]
	v_lshlrev_b32_e32 v101, 16, v62
	v_add_f32_e32 v24, v41, v24
	v_add_f32_e32 v41, v24, v25
	v_mov_b32_e32 v24, v147
	v_mov_b32_e32 v25, v128
	v_pk_mul_f32 v[24:25], v[34:35], v[24:25]
	v_and_b32_e32 v99, 0xffff0000, v62
	v_add_f32_e32 v24, v8, v24
	v_add_f32_e32 v42, v24, v25
	v_pk_mul_f32 v[24:25], v[38:39], v[106:107]
	v_mov_b32_e32 v62, v125
	v_add_f32_e32 v24, v42, v24
	v_add_f32_e32 v42, v24, v25
	v_mov_b32_e32 v24, v149
	v_mov_b32_e32 v25, v126
	v_pk_mul_f32 v[24:25], v[0:1], v[24:25]
	v_mov_b32_e32 v56, v59
	v_add_f32_e32 v24, v9, v24
	v_add_f32_e32 v44, v24, v25
	v_pk_mul_f32 v[24:25], v[4:5], v[102:103]
	v_lshlrev_b32_e32 v117, 16, v60
	v_add_f32_e32 v24, v44, v24
	v_add_f32_e32 v44, v24, v25
	v_mov_b32_e32 v24, v151
	v_mov_b32_e32 v25, v124
	v_pk_mul_f32 v[24:25], v[28:29], v[24:25]
	v_mov_b32_e32 v116, v121
	v_add_f32_e32 v24, v10, v24
	v_add_f32_e32 v46, v24, v25
	v_pk_mul_f32 v[24:25], v[154:155], v[62:63]
	v_and_b32_e32 v113, 0xffff0000, v60
	v_add_f32_e32 v24, v46, v24
	v_add_f32_e32 v46, v24, v25
	v_mov_b32_e32 v24, v153
	v_mov_b32_e32 v25, v58
	v_pk_mul_f32 v[24:25], v[2:3], v[24:25]
	v_mov_b32_e32 v112, v119
	v_add_f32_e32 v24, v11, v24
	v_add_f32_e32 v48, v24, v25
	v_pk_mul_f32 v[24:25], v[6:7], v[56:57]
	v_mov_b32_e32 v108, v115
	v_add_f32_e32 v24, v48, v24
	v_add_f32_e32 v48, v24, v25
	v_cvt_pk_bf16_f32 v24, v26, v27
	v_cvt_pk_bf16_f32 v25, v31, v41
	v_cvt_pk_bf16_f32 v26, v42, v44
	v_cvt_pk_bf16_f32 v27, v46, v48
	ds_write_b128 v30, v[24:27] offset:272
	v_pk_mul_f32 v[24:25], v[64:65], v[136:137]
	v_mov_b32_e32 v104, v111
	v_add_f32_e32 v24, v20, v24
	v_add_f32_e32 v26, v24, v25
	v_pk_mul_f32 v[24:25], v[66:67], v[116:117]
	v_mov_b32_e32 v100, v107
	v_add_f32_e32 v24, v26, v24
	v_add_f32_e32 v26, v24, v25
	v_pk_mul_f32 v[24:25], v[12:13], v[134:135]
	v_mov_b32_e32 v98, v103
	v_add_f32_e32 v24, v21, v24
	v_add_f32_e32 v27, v24, v25
	v_pk_mul_f32 v[24:25], v[16:17], v[112:113]
	v_mov_b32_e32 v96, v63
	v_add_f32_e32 v24, v27, v24
	v_add_f32_e32 v27, v24, v25
	v_pk_mul_f32 v[24:25], v[32:33], v[132:133]
	v_pk_mul_f32 v[12:13], v[12:13], v[118:119]
	v_add_f32_e32 v24, v22, v24
	v_add_f32_e32 v31, v24, v25
	v_pk_mul_f32 v[24:25], v[36:37], v[108:109]
	v_add_f32_e32 v12, v21, v12
	v_add_f32_e32 v24, v31, v24
	v_add_f32_e32 v31, v24, v25
	v_pk_mul_f32 v[24:25], v[14:15], v[130:131]
	v_mov_b32_e32 v54, v113
	v_add_f32_e32 v24, v23, v24
	v_add_f32_e32 v41, v24, v25
	v_pk_mul_f32 v[24:25], v[18:19], v[104:105]
	v_mov_b32_e32 v60, v57
	v_add_f32_e32 v24, v41, v24
	v_add_f32_e32 v41, v24, v25
	v_pk_mul_f32 v[24:25], v[34:35], v[128:129]
	v_add_f32_e32 v21, v12, v13
	v_add_f32_e32 v24, v8, v24
	v_add_f32_e32 v42, v24, v25
	v_pk_mul_f32 v[24:25], v[38:39], v[100:101]
	v_pk_mul_f32 v[12:13], v[16:17], v[54:55]
	v_add_f32_e32 v24, v42, v24
	v_add_f32_e32 v42, v24, v25
	v_pk_mul_f32 v[24:25], v[0:1], v[126:127]
	v_add_f32_e32 v12, v21, v12
	v_add_f32_e32 v24, v9, v24
	v_add_f32_e32 v44, v24, v25
	v_pk_mul_f32 v[24:25], v[4:5], v[98:99]
	v_add_f32_e32 v16, v12, v13
	v_add_f32_e32 v24, v44, v24
	v_add_f32_e32 v44, v24, v25
	v_pk_mul_f32 v[24:25], v[28:29], v[124:125]
	v_pk_mul_f32 v[12:13], v[32:33], v[114:115]
	v_add_f32_e32 v24, v10, v24
	v_add_f32_e32 v46, v24, v25
	v_pk_mul_f32 v[24:25], v[154:155], v[96:97]
	v_pk_mul_f32 v[0:1], v[0:1], v[102:103]
	v_add_f32_e32 v24, v46, v24
	v_add_f32_e32 v46, v24, v25
	v_pk_mul_f32 v[24:25], v[2:3], v[58:59]
	v_add_f32_e32 v12, v22, v12
	v_add_f32_e32 v24, v11, v24
	v_add_f32_e32 v48, v24, v25
	v_pk_mul_f32 v[24:25], v[6:7], v[60:61]
	v_mov_b32_e32 v52, v109
	v_add_f32_e32 v24, v48, v24
	v_add_f32_e32 v48, v24, v25
	v_cvt_pk_bf16_f32 v24, v26, v27
	v_cvt_pk_bf16_f32 v25, v31, v41
	v_cvt_pk_bf16_f32 v26, v42, v44
	v_cvt_pk_bf16_f32 v27, v46, v48
	v_add_f32_e32 v0, v9, v0
	v_mov_b32_e32 v46, v99
	v_add_f32_e32 v17, v12, v13
	v_pk_mul_f32 v[12:13], v[36:37], v[52:53]
	v_add_f32_e32 v9, v0, v1
	v_pk_mul_f32 v[0:1], v[4:5], v[46:47]
	v_add_f32_e32 v12, v17, v12
	v_add_f32_e32 v0, v9, v0
	v_add_f32_e32 v17, v12, v13
	v_pk_mul_f32 v[12:13], v[14:15], v[110:111]
	v_add_f32_e32 v4, v0, v1
	v_pk_mul_f32 v[0:1], v[28:29], v[62:63]
	v_add_f32_e32 v12, v23, v12
	v_mov_b32_e32 v50, v105
	v_add_f32_e32 v0, v10, v0
	v_mov_b32_e32 v44, v97
	v_add_f32_e32 v14, v12, v13
	v_pk_mul_f32 v[12:13], v[18:19], v[50:51]
	v_add_f32_e32 v5, v0, v1
	v_pk_mul_f32 v[0:1], v[154:155], v[44:45]
	v_add_f32_e32 v12, v14, v12
	v_add_f32_e32 v0, v5, v0
	ds_write_b128 v30, v[24:27] offset:544
	v_pk_mul_f32 v[24:25], v[64:65], v[120:121]
	v_add_f32_e32 v14, v12, v13
	v_pk_mul_f32 v[12:13], v[34:35], v[106:107]
	v_add_f32_e32 v5, v0, v1
	v_pk_mul_f32 v[0:1], v[2:3], v[56:57]
	v_add_f32_e32 v20, v20, v24
	v_mov_b32_e32 v122, v117
	v_add_f32_e32 v8, v8, v12
	v_mov_b32_e32 v48, v101
	v_add_f32_e32 v0, v11, v0
	v_mov_b32_e32 v42, v61
	v_add_f32_e32 v20, v20, v25
	v_pk_mul_f32 v[24:25], v[66:67], v[122:123]
	v_add_f32_e32 v8, v8, v13
	v_pk_mul_f32 v[12:13], v[38:39], v[48:49]
	v_add_f32_e32 v2, v0, v1
	v_pk_mul_f32 v[0:1], v[6:7], v[42:43]
	v_and_b32_e32 v164, 15, v75
	v_add_f32_e32 v20, v20, v24
	v_add_f32_e32 v8, v8, v12
	v_add_f32_e32 v0, v2, v0
	v_lshl_or_b32 v48, s4, 4, v164
	s_lshl_b32 s4, s4, 12
	s_ashr_i32 s59, s58, 31
	v_add_f32_e32 v20, v20, v25
	v_add_f32_e32 v8, v8, v13
	v_add_f32_e32 v3, v0, v1
	v_cvt_pk_bf16_f32 v0, v20, v16
	v_cvt_pk_bf16_f32 v1, v17, v14
	v_cvt_pk_bf16_f32 v2, v8, v4
	v_or_b32_e32 v4, 3, v94
	s_add_i32 s8, s4, 0
	s_lshl_b64 s[4:5], s[58:59], 14
	v_cvt_pk_bf16_f32 v3, v5, v3
	v_mad_u64_u32 v[4:5], s[6:7], v4, s67, v[40:41]
	v_bfe_u32 v99, v75, 4, 2
	v_ashrrev_i32_e32 v49, 31, v48
	s_add_u32 s4, s37, s4
	ds_write_b128 v4, v[0:3]
	v_lshlrev_b32_e32 v68, 4, v99
	v_lshl_add_u64 v[0:1], v[48:49], 0, s[38:39]
	s_addc_u32 s5, s41, s5
	s_or_b32 s6, s38, 0x800
	s_mov_b32 s7, s39
	v_lshl_add_u64 v[160:161], s[34:35], 0, v[68:69]
	v_lshlrev_b64 v[0:1], 8, v[0:1]
	v_lshl_add_u64 v[8:9], v[48:49], 0, s[6:7]
	v_lshl_add_u64 v[66:67], v[160:161], 0, v[0:1]
	v_add_u32_e32 v165, 0, v68
	v_lshlrev_b64 v[8:9], 8, v[8:9]
	s_waitcnt lgkmcnt(0)
	s_barrier
; DI void lru_tile(const Params& p, unsigned char* shm, int c, int nb, const LruPar par) {
;     ...
;         for (int s = 0; s < 4; ++s)
; #pragma unroll
;             for (int gt = 0; gt < 2; ++gt) bfr[s][gt] = *(const bf16x8*)(LWT + ((size_t)((d * 2 + gt) * 16 + nb) * 128 + chl) * 128 + s * 32 + q * 8);
; #pragma unroll
;         for (int s = 0; s < 4; ++s) {
; #pragma unroll
;             for (int rt = 0; rt < 8; ++rt) {
;                 const bf16x8 af = *(const bf16x8*)(UB + (rt * 16 + col) * LDU + s * 32 + q * 8);
; #pragma unroll
;                 for (int gt = 0; gt < 2; ++gt) acc[gt][rt] = __builtin_amdgcn_mfma_f32_16x16x32_bf16(af, bfr[s][gt], acc[gt][rt], 0, 0, 0);
;             }
;             __builtin_amdgcn_sched_barrier(0);
;         }
	v_mad_u32_u24 v68, v164, s67, v165
	v_lshl_add_u64 v[96:97], v[160:161], 0, v[8:9]
	ds_read_b128 v[4:7], v68
	ds_read_b128 v[12:15], v68 offset:4352
	ds_read_b128 v[32:35], v68 offset:8704
	ds_read_b128 v[36:39], v68 offset:13056
	ds_read_b128 v[50:53], v68 offset:17408
	ds_read_b128 v[54:57], v68 offset:21760
	ds_read_b128 v[58:61], v68 offset:26112
	ds_read_b128 v[116:119], v68 offset:30464
	s_waitcnt vmcnt(7) lgkmcnt(7)
	v_mfma_f32_16x16x32_bf16 v[16:19], v[4:7], v[208:211], 0
	v_cmp_eq_u32_e64 s[10:11], 0, v99
	s_waitcnt lgkmcnt(6)
	v_mfma_f32_16x16x32_bf16 v[28:31], v[12:15], v[208:211], 0
	s_waitcnt lgkmcnt(5)
	v_mfma_f32_16x16x32_bf16 v[40:43], v[32:35], v[208:211], 0
	s_waitcnt lgkmcnt(4)
	v_mfma_f32_16x16x32_bf16 v[44:47], v[36:39], v[208:211], 0
	s_waitcnt lgkmcnt(3)
	v_mfma_f32_16x16x32_bf16 v[62:65], v[50:53], v[208:211], 0
	s_waitcnt vmcnt(5)
	v_mfma_f32_16x16x32_bf16 v[50:53], v[50:53], v[212:215], 0
	s_waitcnt lgkmcnt(2)
	v_mfma_f32_16x16x32_bf16 v[100:103], v[54:57], v[208:211], 0
	v_mfma_f32_16x16x32_bf16 v[104:107], v[54:57], v[212:215], 0
	v_lshl_add_u32 v55, v164, 3, s8
	v_add_u32_e32 v54, s38, v48
	s_waitcnt lgkmcnt(1)
	v_mfma_f32_16x16x32_bf16 v[120:123], v[58:61], v[208:211], 0
	v_mfma_f32_16x16x32_bf16 v[132:135], v[58:61], v[212:215], 0
	v_add_u32_e32 v59, 0x19800, v55
	v_ashrrev_i32_e32 v55, 31, v54
	v_lshlrev_b32_e32 v58, 1, v48
	s_waitcnt lgkmcnt(0)
	v_mfma_f32_16x16x32_bf16 v[0:3], v[116:119], v[208:211], 0
	v_lshl_add_u32 v61, v99, 7, v59
	v_lshl_add_u64 v[56:57], v[54:55], 3, s[4:5]
	v_mfma_f32_16x16x32_bf16 v[4:7], v[4:7], v[212:215], 0
	v_mfma_f32_16x16x32_bf16 v[12:15], v[12:15], v[212:215], 0
	v_mfma_f32_16x16x32_bf16 v[32:35], v[32:35], v[212:215], 0
	v_mfma_f32_16x16x32_bf16 v[36:39], v[36:39], v[212:215], 0
	v_mfma_f32_16x16x32_bf16 v[20:23], v[116:119], v[212:215], 0
	ds_read_b128 v[116:119], v68 offset:64
	ds_read_b128 v[136:139], v68 offset:4416
	s_waitcnt lgkmcnt(1)
	v_mfma_f32_16x16x32_bf16 v[16:19], v[116:119], v[216:219], v[16:19]
	s_waitcnt vmcnt(4)
	v_mfma_f32_16x16x32_bf16 v[4:7], v[116:119], v[220:223], v[4:7]
	s_waitcnt lgkmcnt(0)
	v_mfma_f32_16x16x32_bf16 v[28:31], v[136:139], v[216:219], v[28:31]
	v_mfma_f32_16x16x32_bf16 v[12:15], v[136:139], v[220:223], v[12:15]
	ds_read_b128 v[116:119], v68 offset:8768
	ds_read_b128 v[136:139], v68 offset:13120
	s_waitcnt lgkmcnt(1)
	v_mfma_f32_16x16x32_bf16 v[40:43], v[116:119], v[216:219], v[40:43]
	v_mfma_f32_16x16x32_bf16 v[32:35], v[116:119], v[220:223], v[32:35]
	s_waitcnt lgkmcnt(0)
	v_mfma_f32_16x16x32_bf16 v[44:47], v[136:139], v[216:219], v[44:47]
	v_mfma_f32_16x16x32_bf16 v[36:39], v[136:139], v[220:223], v[36:39]
	ds_read_b128 v[116:119], v68 offset:17472
	ds_read_b128 v[136:139], v68 offset:21824
	s_waitcnt lgkmcnt(1)
	v_mfma_f32_16x16x32_bf16 v[62:65], v[116:119], v[216:219], v[62:65]
	v_mfma_f32_16x16x32_bf16 v[50:53], v[116:119], v[220:223], v[50:53]
	s_waitcnt lgkmcnt(0)
	v_mfma_f32_16x16x32_bf16 v[100:103], v[136:139], v[216:219], v[100:103]
	v_mfma_f32_16x16x32_bf16 v[104:107], v[136:139], v[220:223], v[104:107]
	ds_read_b128 v[116:119], v68 offset:26176
	ds_read_b128 v[136:139], v68 offset:30528
	s_waitcnt lgkmcnt(1)
	v_mfma_f32_16x16x32_bf16 v[120:123], v[116:119], v[216:219], v[120:123]
	v_mfma_f32_16x16x32_bf16 v[116:119], v[116:119], v[220:223], v[132:135]
	s_waitcnt lgkmcnt(0)
	v_mfma_f32_16x16x32_bf16 v[0:3], v[136:139], v[216:219], v[0:3]
	v_mfma_f32_16x16x32_bf16 v[8:11], v[136:139], v[220:223], v[20:23]
	s_nop 2
	ds_read_b128 v[20:23], v68 offset:128
	ds_read_b128 v[24:27], v68 offset:4480
	s_waitcnt vmcnt(3) lgkmcnt(1)
	v_mfma_f32_16x16x32_bf16 v[16:19], v[20:23], v[224:227], v[16:19]
	s_waitcnt vmcnt(1)
	v_mfma_f32_16x16x32_bf16 v[4:7], v[20:23], v[228:231], v[4:7]
	s_waitcnt lgkmcnt(0)
	v_mfma_f32_16x16x32_bf16 v[20:23], v[24:27], v[224:227], v[28:31]
	v_mfma_f32_16x16x32_bf16 v[12:15], v[24:27], v[228:231], v[12:15]
	ds_read_b128 v[24:27], v68 offset:8832
	s_nop 0
	ds_read_b128 v[28:31], v68 offset:13184
	s_waitcnt lgkmcnt(1)
	v_mfma_f32_16x16x32_bf16 v[40:43], v[24:27], v[224:227], v[40:43]
	v_mfma_f32_16x16x32_bf16 v[24:27], v[24:27], v[228:231], v[32:35]
	s_waitcnt lgkmcnt(0)
	v_mfma_f32_16x16x32_bf16 v[32:35], v[28:31], v[224:227], v[44:47]
	v_mfma_f32_16x16x32_bf16 v[28:31], v[28:31], v[228:231], v[36:39]
	s_nop 2
	ds_read_b128 v[36:39], v68 offset:17536
	ds_read_b128 v[44:47], v68 offset:21888
	s_waitcnt lgkmcnt(1)
	v_mfma_f32_16x16x32_bf16 v[62:65], v[36:39], v[224:227], v[62:65]
	v_mfma_f32_16x16x32_bf16 v[50:53], v[36:39], v[228:231], v[50:53]
	s_waitcnt lgkmcnt(0)
	v_mfma_f32_16x16x32_bf16 v[100:103], v[44:47], v[224:227], v[100:103]
	v_mfma_f32_16x16x32_bf16 v[104:107], v[44:47], v[228:231], v[104:107]
	ds_read_b128 v[36:39], v68 offset:26240
	ds_read_b128 v[44:47], v68 offset:30592
	s_waitcnt lgkmcnt(1)
	v_mfma_f32_16x16x32_bf16 v[120:123], v[36:39], v[224:227], v[120:123]
	v_mfma_f32_16x16x32_bf16 v[116:119], v[36:39], v[228:231], v[116:119]
	s_waitcnt lgkmcnt(0)
	v_mfma_f32_16x16x32_bf16 v[0:3], v[44:47], v[224:227], v[0:3]
	v_mfma_f32_16x16x32_bf16 v[108:111], v[44:47], v[228:231], v[8:11]
	s_nop 2
	ds_read_b128 v[8:11], v68 offset:192
	ds_read_b128 v[36:39], v68 offset:4544
	s_waitcnt lgkmcnt(1)
	v_mfma_f32_16x16x32_bf16 v[124:127], v[8:11], v[232:235], v[16:19]
	s_waitcnt vmcnt(0)
	v_mfma_f32_16x16x32_bf16 v[132:135], v[8:11], v[236:239], v[4:7]
	s_nop 2
	ds_read_b128 v[4:7], v68 offset:8896
	ds_read_b128 v[8:11], v68 offset:13248
	s_waitcnt lgkmcnt(2)
	v_mfma_f32_16x16x32_bf16 v[136:139], v[36:39], v[232:235], v[20:23]
	v_mfma_f32_16x16x32_bf16 v[140:143], v[36:39], v[236:239], v[12:15]
	s_waitcnt lgkmcnt(1)
; DI float bf2f(unsigned short b) { return __uint_as_float(((unsigned)b) << 16); }
; DI float ex2(float x) { return __builtin_amdgcn_exp2f(x); }
; DI float rcpf_(float x) { return __builtin_amdgcn_rcpf(x); }
; DI void lru_tile(const Params& p, unsigned char* shm, int c, int nb, const LruPar par) {
;     ...
;                 for (int gt = 0; gt < 2; ++gt) acc[gt][rt] = __builtin_amdgcn_mfma_f32_16x16x32_bf16(af, bfr[s][gt], acc[gt][rt], 0, 0, 0);
;             }
;             __builtin_amdgcn_sched_barrier(0);
;         }
;         const f32x2 nl2 = {-LOG2E, -LOG2E}, nbr2 = {par.nbr[d], par.nbr[d]}, nbi2 = {par.nbi[d], par.nbi[d]}, cd2 = {par.cdec[d], par.cdec[d]}, one2 = {1.f, 1.f};
;         float hl[8][4], pc[8][4];
; #pragma unroll
;         for (int rt = 0; rt < 8; ++rt) {
;             float av[4], bv[4];
; #pragma unroll
;             for (int jp = 0; jp < 2; ++jp) {
;                 const f32x2 xr = {acc[0][rt][2 * jp], acc[0][rt][2 * jp + 1]}, xi = {acc[1][rt][2 * jp], acc[1][rt][2 * jp + 1]};
;                 f32x2 er = xr * nl2 + nbr2, ei = xi * nl2 + nbi2;
;                 er = (f32x2){ex2(er[0]), ex2(er[1])} + one2; ei = (f32x2){ex2(ei[0]), ex2(ei[1])} + one2;
;                 const f32x2 r = {rcpf_(er[0]), rcpf_(er[1])}, ig = {rcpf_(ei[0]), rcpf_(ei[1])};
;                 const f32x2 la = r * cd2;
;                 const f32x2 a = {ex2(la[0]), ex2(la[1])};
;                 const f32x2 om = one2 - a * a;
;                 const f32x2 sc = {__builtin_amdgcn_sqrtf(om[0]), __builtin_amdgcn_sqrtf(om[1])};
;                 const f32x2 u2 = {bf2f(UB[(rt * 16 + 4 * q + 2 * jp) * LDU + chl]), bf2f(UB[(rt * 16 + 4 * q + 2 * jp + 1) * LDU + chl])};
;                 const f32x2 b2 = sc * ig * u2;
;                 av[2 * jp] = a[0]; av[2 * jp + 1] = a[1]; bv[2 * jp] = b2[0]; bv[2 * jp + 1] = b2[1];
;             }
;             float h = 0.f, P = 1.f;
;             if (d == 0) {
; #pragma unroll
;                 for (int j = 0; j < 4; ++j) { h = fmaf(av[j], h, bv[j]); P *= av[j]; hl[rt][j] = h; pc[rt][j] = P; }
	v_mfma_f32_16x16x32_bf16 v[44:47], v[4:7], v[232:235], v[40:43]
	v_mfma_f32_16x16x32_bf16 v[40:43], v[4:7], v[236:239], v[24:27]
	s_waitcnt lgkmcnt(0)
	v_mfma_f32_16x16x32_bf16 v[36:39], v[8:11], v[232:235], v[32:35]
	v_mfma_f32_16x16x32_bf16 v[32:35], v[8:11], v[236:239], v[28:31]
	ds_read_b128 v[4:7], v68 offset:17600
	ds_read_b128 v[8:11], v68 offset:21952
	s_waitcnt lgkmcnt(1)
	v_mfma_f32_16x16x32_bf16 v[28:31], v[4:7], v[232:235], v[62:65]
	v_mfma_f32_16x16x32_bf16 v[24:27], v[4:7], v[236:239], v[50:53]
	ds_read_b128 v[4:7], v68 offset:26304
	s_nop 1
	ds_read_b128 v[50:53], v68 offset:30656
	s_waitcnt lgkmcnt(2)
	v_mfma_f32_16x16x32_bf16 v[20:23], v[8:11], v[232:235], v[100:103]
	v_mfma_f32_16x16x32_bf16 v[16:19], v[8:11], v[236:239], v[104:107]
	s_waitcnt lgkmcnt(1)
	v_mfma_f32_16x16x32_bf16 v[12:15], v[4:7], v[232:235], v[120:123]
	v_mfma_f32_16x16x32_bf16 v[8:11], v[4:7], v[236:239], v[116:119]
	s_waitcnt lgkmcnt(0)
	v_mfma_f32_16x16x32_bf16 v[4:7], v[50:53], v[232:235], v[0:3]
	v_mfma_f32_16x16x32_bf16 v[0:3], v[50:53], v[236:239], v[108:111]
	v_fma_f32 v52, -v126, s50, v82
	v_fma_f32 v53, -v127, s50, v82
	v_pk_fma_f32 v[54:55], v[134:135], s[50:51], v[86:87] op_sel_hi:[1,0,0] neg_lo:[1,0,0] neg_hi:[1,0,0]
	v_exp_f32_e32 v52, v52
	v_exp_f32_e32 v53, v53
	v_pk_fma_f32 v[50:51], v[124:125], s[50:51], v[82:83] op_sel_hi:[1,0,0] neg_lo:[1,0,0] neg_hi:[1,0,0]
	v_exp_f32_e32 v54, v54
	v_exp_f32_e32 v55, v55
	v_pk_add_f32 v[52:53], v[52:53], 1.0 op_sel_hi:[1,0]
	v_exp_f32_e32 v50, v50
	v_rcp_f32_e32 v52, v52
	v_rcp_f32_e32 v53, v53
	v_exp_f32_e32 v51, v51
	v_mul_u32_u24_e32 v95, 0x220, v99
	v_lshlrev_b32_e32 v60, 1, v95
	v_pk_mul_f32 v[52:53], v[92:93], v[52:53] op_sel_hi:[0,1]
	v_exp_f32_e32 v62, v52
	v_exp_f32_e32 v63, v53
	v_pk_add_f32 v[52:53], v[54:55], 1.0 op_sel_hi:[1,0]
	v_pk_add_f32 v[50:51], v[50:51], 1.0 op_sel_hi:[1,0]
	v_rcp_f32_e32 v52, v52
	v_pk_fma_f32 v[54:55], v[62:63], v[62:63], 1.0 op_sel_hi:[1,1,0] neg_lo:[1,0,0] neg_hi:[1,0,0]
	v_rcp_f32_e32 v53, v53
	v_sqrt_f32_e32 v54, v54
	v_sqrt_f32_e32 v55, v55
	v_rcp_f32_e32 v50, v50
	v_rcp_f32_e32 v51, v51
	v_add3_u32 v68, 0, v58, v60
	v_pk_mul_f32 v[52:53], v[52:53], v[54:55]
	v_pk_fma_f32 v[54:55], v[132:133], s[50:51], v[86:87] op_sel_hi:[1,0,0] neg_lo:[1,0,0] neg_hi:[1,0,0]
	v_pk_mul_f32 v[50:51], v[92:93], v[50:51] op_sel_hi:[0,1]
	v_exp_f32_e32 v54, v54
	v_exp_f32_e32 v55, v55
	v_exp_f32_e32 v50, v50
	v_exp_f32_e32 v51, v51
	v_add3_u32 v97, 0, v60, v58
	ds_read_u16 v58, v68 offset:544
	ds_read_u16 v60, v97 offset:816
	v_pk_add_f32 v[54:55], v[54:55], 1.0 op_sel_hi:[1,0]
	ds_read_u16 v96, v97 offset:272
	ds_read_u16 v98, v68
	v_rcp_f32_e32 v64, v54
	v_rcp_f32_e32 v65, v55
	v_pk_fma_f32 v[54:55], v[50:51], v[50:51], 1.0 op_sel_hi:[1,1,0] neg_lo:[1,0,0] neg_hi:[1,0,0]
	s_nop 0
	v_sqrt_f32_e32 v66, v54
	v_sqrt_f32_e32 v67, v55
	s_waitcnt lgkmcnt(3)
	v_lshlrev_b32_e32 v54, 16, v58
	s_waitcnt lgkmcnt(2)
	v_lshlrev_b32_e32 v55, 16, v60
	v_pk_mul_f32 v[54:55], v[52:53], v[54:55]
	v_pk_mul_f32 v[52:53], v[64:65], v[66:67]
	s_waitcnt lgkmcnt(0)
	v_lshlrev_b32_e32 v64, 16, v98
	v_lshlrev_b32_e32 v65, 16, v96
	v_pk_mul_f32 v[52:53], v[52:53], v[64:65]
	s_nop 0
	v_fma_f32 v52, 0, v50, v52
	v_fmac_f32_e32 v53, v51, v52
	v_mul_f32_e32 v51, v50, v51
	v_fma_f32 v58, v62, v53, v54
	v_mul_f32_e32 v60, v62, v51
	v_fmac_f32_e32 v55, v63, v58
	v_mul_f32_e32 v54, v63, v60
	ds_write_b64 v61, v[54:55]
	v_pk_fma_f32 v[64:65], v[138:139], s[50:51], v[82:83] op_sel_hi:[1,0,0] neg_lo:[1,0,0] neg_hi:[1,0,0]
	v_pk_fma_f32 v[66:67], v[142:143], s[50:51], v[86:87] op_sel_hi:[1,0,0] neg_lo:[1,0,0] neg_hi:[1,0,0]
	v_exp_f32_e32 v64, v64
	v_exp_f32_e32 v65, v65
	v_pk_fma_f32 v[62:63], v[136:137], s[50:51], v[82:83] op_sel_hi:[1,0,0] neg_lo:[1,0,0] neg_hi:[1,0,0]
	v_exp_f32_e32 v66, v66
	v_exp_f32_e32 v67, v67
	v_pk_add_f32 v[64:65], v[64:65], 1.0 op_sel_hi:[1,0]
	v_exp_f32_e32 v62, v62
	v_rcp_f32_e32 v64, v64
	v_rcp_f32_e32 v65, v65
	v_exp_f32_e32 v63, v63
	ds_read_u16 v96, v68 offset:4896
	ds_read_u16 v98, v97 offset:5168
	ds_read_u16 v106, v97 offset:4624
	ds_read_u16 v107, v68 offset:4352
	v_pk_mul_f32 v[64:65], v[92:93], v[64:65] op_sel_hi:[0,1]
	v_exp_f32_e32 v100, v64
	v_exp_f32_e32 v101, v65
	v_pk_add_f32 v[64:65], v[66:67], 1.0 op_sel_hi:[1,0]
	v_pk_add_f32 v[62:63], v[62:63], 1.0 op_sel_hi:[1,0]
	v_rcp_f32_e32 v64, v64
	v_pk_fma_f32 v[66:67], v[100:101], v[100:101], 1.0 op_sel_hi:[1,1,0] neg_lo:[1,0,0] neg_hi:[1,0,0]
	v_rcp_f32_e32 v65, v65
	v_sqrt_f32_e32 v66, v66
	v_sqrt_f32_e32 v67, v67
	v_rcp_f32_e32 v62, v62
	v_rcp_f32_e32 v63, v63
	v_pk_mul_f32 v[64:65], v[64:65], v[66:67]
	v_pk_fma_f32 v[66:67], v[140:141], s[50:51], v[86:87] op_sel_hi:[1,0,0] neg_lo:[1,0,0] neg_hi:[1,0,0]
	v_pk_mul_f32 v[62:63], v[92:93], v[62:63] op_sel_hi:[0,1]
	v_exp_f32_e32 v66, v66
	v_exp_f32_e32 v67, v67
	v_exp_f32_e32 v62, v62
	v_exp_f32_e32 v63, v63
	v_pk_add_f32 v[66:67], v[66:67], 1.0 op_sel_hi:[1,0]
	s_nop 0
	v_rcp_f32_e32 v102, v66
	v_rcp_f32_e32 v103, v67
	v_pk_fma_f32 v[66:67], v[62:63], v[62:63], 1.0 op_sel_hi:[1,1,0] neg_lo:[1,0,0] neg_hi:[1,0,0]
	s_nop 0
	v_sqrt_f32_e32 v104, v66
	v_sqrt_f32_e32 v105, v67
	s_waitcnt lgkmcnt(3)
	v_lshlrev_b32_e32 v66, 16, v96
	s_waitcnt lgkmcnt(2)
	v_lshlrev_b32_e32 v67, 16, v98
	v_pk_mul_f32 v[66:67], v[64:65], v[66:67]
	v_pk_mul_f32 v[64:65], v[102:103], v[104:105]
	s_waitcnt lgkmcnt(0)
; DI float bf2f(unsigned short b) { return __uint_as_float(((unsigned)b) << 16); }
; DI float ex2(float x) { return __builtin_amdgcn_exp2f(x); }
; DI float rcpf_(float x) { return __builtin_amdgcn_rcpf(x); }
; DI void lru_tile(const Params& p, unsigned char* shm, int c, int nb, const LruPar par) {
;     ...
;         const f32x2 nl2 = {-LOG2E, -LOG2E}, nbr2 = {par.nbr[d], par.nbr[d]}, nbi2 = {par.nbi[d], par.nbi[d]}, cd2 = {par.cdec[d], par.cdec[d]}, one2 = {1.f, 1.f};
;         float hl[8][4], pc[8][4];
; #pragma unroll
;         for (int rt = 0; rt < 8; ++rt) {
;             float av[4], bv[4];
; #pragma unroll
;             for (int jp = 0; jp < 2; ++jp) {
;                 const f32x2 xr = {acc[0][rt][2 * jp], acc[0][rt][2 * jp + 1]}, xi = {acc[1][rt][2 * jp], acc[1][rt][2 * jp + 1]};
;                 f32x2 er = xr * nl2 + nbr2, ei = xi * nl2 + nbi2;
;                 er = (f32x2){ex2(er[0]), ex2(er[1])} + one2; ei = (f32x2){ex2(ei[0]), ex2(ei[1])} + one2;
;                 const f32x2 r = {rcpf_(er[0]), rcpf_(er[1])}, ig = {rcpf_(ei[0]), rcpf_(ei[1])};
;                 const f32x2 la = r * cd2;
;                 const f32x2 a = {ex2(la[0]), ex2(la[1])};
;                 const f32x2 om = one2 - a * a;
;                 const f32x2 sc = {__builtin_amdgcn_sqrtf(om[0]), __builtin_amdgcn_sqrtf(om[1])};
;                 const f32x2 u2 = {bf2f(UB[(rt * 16 + 4 * q + 2 * jp) * LDU + chl]), bf2f(UB[(rt * 16 + 4 * q + 2 * jp + 1) * LDU + chl])};
;                 const f32x2 b2 = sc * ig * u2;
;                 av[2 * jp] = a[0]; av[2 * jp + 1] = a[1]; bv[2 * jp] = b2[0]; bv[2 * jp + 1] = b2[1];
;             }
;             float h = 0.f, P = 1.f;
;             if (d == 0) {
; #pragma unroll
;                 for (int j = 0; j < 4; ++j) { h = fmaf(av[j], h, bv[j]); P *= av[j]; hl[rt][j] = h; pc[rt][j] = P; }
;             } else {
; #pragma unroll
;                 for (int j = 3; j >= 0; --j) { h = fmaf(av[j], h, bv[j]); P *= av[j]; hl[rt][j] = h; pc[rt][j] = P; }
;             }
;             AG[(rt * 4 + q) * 16 + col] = (f32x2){P, h};
;             __builtin_amdgcn_sched_barrier(0);
	v_lshlrev_b32_e32 v102, 16, v107
	v_lshlrev_b32_e32 v103, 16, v106
	v_pk_mul_f32 v[64:65], v[64:65], v[102:103]
	s_nop 0
	v_fma_f32 v64, 0, v62, v64
	v_fmac_f32_e32 v65, v63, v64
	v_mul_f32_e32 v63, v62, v63
	v_fma_f32 v96, v100, v65, v66
	v_mul_f32_e32 v98, v100, v63
	v_fmac_f32_e32 v67, v101, v96
	v_mul_f32_e32 v66, v101, v98
	ds_write_b64 v61, v[66:67] offset:512
	v_pk_fma_f32 v[46:47], v[46:47], s[50:51], v[82:83] op_sel_hi:[1,0,0] neg_lo:[1,0,0] neg_hi:[1,0,0]
	v_pk_fma_f32 v[44:45], v[44:45], s[50:51], v[82:83] op_sel_hi:[1,0,0] neg_lo:[1,0,0] neg_hi:[1,0,0]
	v_exp_f32_e32 v46, v46
	v_exp_f32_e32 v47, v47
	v_exp_f32_e32 v44, v44
	v_exp_f32_e32 v45, v45
	v_pk_fma_f32 v[42:43], v[42:43], s[50:51], v[86:87] op_sel_hi:[1,0,0] neg_lo:[1,0,0] neg_hi:[1,0,0]
	v_pk_add_f32 v[46:47], v[46:47], 1.0 op_sel_hi:[1,0]
	v_exp_f32_e32 v42, v42
	v_rcp_f32_e32 v46, v46
	v_rcp_f32_e32 v47, v47
	v_pk_add_f32 v[44:45], v[44:45], 1.0 op_sel_hi:[1,0]
	v_exp_f32_e32 v43, v43
	v_rcp_f32_e32 v44, v44
	v_pk_mul_f32 v[46:47], v[92:93], v[46:47] op_sel_hi:[0,1]
	v_exp_f32_e32 v46, v46
	v_exp_f32_e32 v47, v47
	v_rcp_f32_e32 v45, v45
	v_pk_add_f32 v[42:43], v[42:43], 1.0 op_sel_hi:[1,0]
	v_pk_fma_f32 v[40:41], v[40:41], s[50:51], v[86:87] op_sel_hi:[1,0,0] neg_lo:[1,0,0] neg_hi:[1,0,0]
	v_pk_fma_f32 v[100:101], v[46:47], v[46:47], 1.0 op_sel_hi:[1,1,0] neg_lo:[1,0,0] neg_hi:[1,0,0]
	v_rcp_f32_e32 v42, v42
	v_rcp_f32_e32 v43, v43
	v_sqrt_f32_e32 v102, v100
	v_sqrt_f32_e32 v103, v101
	v_pk_mul_f32 v[44:45], v[92:93], v[44:45] op_sel_hi:[0,1]
	v_exp_f32_e32 v100, v44
	v_exp_f32_e32 v40, v40
	v_exp_f32_e32 v41, v41
	v_exp_f32_e32 v101, v45
	v_pk_mul_f32 v[42:43], v[42:43], v[102:103]
	ds_read_u16 v102, v68 offset:9248
	ds_read_u16 v103, v97 offset:9520
	v_pk_add_f32 v[40:41], v[40:41], 1.0 op_sel_hi:[1,0]
	v_pk_fma_f32 v[44:45], v[100:101], v[100:101], 1.0 op_sel_hi:[1,1,0] neg_lo:[1,0,0] neg_hi:[1,0,0]
	ds_read_u16 v106, v97 offset:8976
	ds_read_u16 v107, v68 offset:8704
	v_rcp_f32_e32 v40, v40
	v_rcp_f32_e32 v41, v41
	v_sqrt_f32_e32 v44, v44
	v_sqrt_f32_e32 v45, v45
	s_waitcnt lgkmcnt(3)
	v_lshlrev_b32_e32 v102, 16, v102
	s_waitcnt lgkmcnt(2)
	v_lshlrev_b32_e32 v103, 16, v103
	v_pk_mul_f32 v[104:105], v[42:43], v[102:103]
	v_pk_mul_f32 v[40:41], v[40:41], v[44:45]
	s_waitcnt lgkmcnt(0)
	v_lshlrev_b32_e32 v42, 16, v107
	v_lshlrev_b32_e32 v43, 16, v106
	v_pk_mul_f32 v[102:103], v[40:41], v[42:43]
	s_nop 0
	v_fma_f32 v102, 0, v100, v102
	v_fmac_f32_e32 v103, v101, v102
	v_mul_f32_e32 v101, v100, v101
	v_fma_f32 v106, v46, v103, v104
	v_mul_f32_e32 v108, v46, v101
	v_fmac_f32_e32 v105, v47, v106
	v_mul_f32_e32 v104, v47, v108
	ds_write_b64 v61, v[104:105] offset:1024
	v_pk_fma_f32 v[38:39], v[38:39], s[50:51], v[82:83] op_sel_hi:[1,0,0] neg_lo:[1,0,0] neg_hi:[1,0,0]
	v_pk_fma_f32 v[36:37], v[36:37], s[50:51], v[82:83] op_sel_hi:[1,0,0] neg_lo:[1,0,0] neg_hi:[1,0,0]
	v_exp_f32_e32 v38, v38
	v_exp_f32_e32 v39, v39
	v_exp_f32_e32 v36, v36
	v_exp_f32_e32 v37, v37
	v_pk_fma_f32 v[34:35], v[34:35], s[50:51], v[86:87] op_sel_hi:[1,0,0] neg_lo:[1,0,0] neg_hi:[1,0,0]
	v_pk_add_f32 v[38:39], v[38:39], 1.0 op_sel_hi:[1,0]
	v_exp_f32_e32 v34, v34
	v_rcp_f32_e32 v38, v38
	v_rcp_f32_e32 v39, v39
	v_pk_add_f32 v[36:37], v[36:37], 1.0 op_sel_hi:[1,0]
	v_exp_f32_e32 v35, v35
	v_rcp_f32_e32 v36, v36
	v_pk_mul_f32 v[38:39], v[92:93], v[38:39] op_sel_hi:[0,1]
	v_exp_f32_e32 v38, v38
	v_exp_f32_e32 v39, v39
	v_rcp_f32_e32 v37, v37
	v_pk_add_f32 v[34:35], v[34:35], 1.0 op_sel_hi:[1,0]
	v_pk_fma_f32 v[32:33], v[32:33], s[50:51], v[86:87] op_sel_hi:[1,0,0] neg_lo:[1,0,0] neg_hi:[1,0,0]
	v_pk_fma_f32 v[40:41], v[38:39], v[38:39], 1.0 op_sel_hi:[1,1,0] neg_lo:[1,0,0] neg_hi:[1,0,0]
	v_rcp_f32_e32 v34, v34
	v_rcp_f32_e32 v35, v35
	v_sqrt_f32_e32 v40, v40
	v_sqrt_f32_e32 v41, v41
	v_pk_mul_f32 v[36:37], v[92:93], v[36:37] op_sel_hi:[0,1]
	v_exp_f32_e32 v110, v36
	v_exp_f32_e32 v32, v32
	v_exp_f32_e32 v33, v33
	v_exp_f32_e32 v111, v37
	v_pk_mul_f32 v[34:35], v[34:35], v[40:41]
	ds_read_u16 v40, v68 offset:13600
	ds_read_u16 v41, v97 offset:13872
	v_pk_add_f32 v[32:33], v[32:33], 1.0 op_sel_hi:[1,0]
	v_pk_fma_f32 v[36:37], v[110:111], v[110:111], 1.0 op_sel_hi:[1,1,0] neg_lo:[1,0,0] neg_hi:[1,0,0]
	ds_read_u16 v42, v97 offset:13328
	ds_read_u16 v43, v68 offset:13056
	v_rcp_f32_e32 v32, v32
	v_rcp_f32_e32 v33, v33
	v_sqrt_f32_e32 v36, v36
	v_sqrt_f32_e32 v37, v37
	s_waitcnt lgkmcnt(3)
	v_lshlrev_b32_e32 v40, 16, v40
	s_waitcnt lgkmcnt(2)
	v_lshlrev_b32_e32 v41, 16, v41
	v_pk_mul_f32 v[114:115], v[34:35], v[40:41]
	v_pk_mul_f32 v[32:33], v[32:33], v[36:37]
	s_waitcnt lgkmcnt(0)
; DI float bf2f(unsigned short b) { return __uint_as_float(((unsigned)b) << 16); }
; DI float ex2(float x) { return __builtin_amdgcn_exp2f(x); }
; DI float rcpf_(float x) { return __builtin_amdgcn_rcpf(x); }
; DI void lru_tile(const Params& p, unsigned char* shm, int c, int nb, const LruPar par) {
;     ...
;         const f32x2 nl2 = {-LOG2E, -LOG2E}, nbr2 = {par.nbr[d], par.nbr[d]}, nbi2 = {par.nbi[d], par.nbi[d]}, cd2 = {par.cdec[d], par.cdec[d]}, one2 = {1.f, 1.f};
;         float hl[8][4], pc[8][4];
; #pragma unroll
;         for (int rt = 0; rt < 8; ++rt) {
;             float av[4], bv[4];
; #pragma unroll
;             for (int jp = 0; jp < 2; ++jp) {
;                 const f32x2 xr = {acc[0][rt][2 * jp], acc[0][rt][2 * jp + 1]}, xi = {acc[1][rt][2 * jp], acc[1][rt][2 * jp + 1]};
;                 f32x2 er = xr * nl2 + nbr2, ei = xi * nl2 + nbi2;
;                 er = (f32x2){ex2(er[0]), ex2(er[1])} + one2; ei = (f32x2){ex2(ei[0]), ex2(ei[1])} + one2;
;                 const f32x2 r = {rcpf_(er[0]), rcpf_(er[1])}, ig = {rcpf_(ei[0]), rcpf_(ei[1])};
;                 const f32x2 la = r * cd2;
;                 const f32x2 a = {ex2(la[0]), ex2(la[1])};
;                 const f32x2 om = one2 - a * a;
;                 const f32x2 sc = {__builtin_amdgcn_sqrtf(om[0]), __builtin_amdgcn_sqrtf(om[1])};
;                 const f32x2 u2 = {bf2f(UB[(rt * 16 + 4 * q + 2 * jp) * LDU + chl]), bf2f(UB[(rt * 16 + 4 * q + 2 * jp + 1) * LDU + chl])};
;                 const f32x2 b2 = sc * ig * u2;
;                 av[2 * jp] = a[0]; av[2 * jp + 1] = a[1]; bv[2 * jp] = b2[0]; bv[2 * jp + 1] = b2[1];
;             }
;             float h = 0.f, P = 1.f;
;             if (d == 0) {
; #pragma unroll
;                 for (int j = 0; j < 4; ++j) { h = fmaf(av[j], h, bv[j]); P *= av[j]; hl[rt][j] = h; pc[rt][j] = P; }
;             } else {
; #pragma unroll
;                 for (int j = 3; j >= 0; --j) { h = fmaf(av[j], h, bv[j]); P *= av[j]; hl[rt][j] = h; pc[rt][j] = P; }
;             }
;             AG[(rt * 4 + q) * 16 + col] = (f32x2){P, h};
;             __builtin_amdgcn_sched_barrier(0);
	v_lshlrev_b32_e32 v34, 16, v43
	v_lshlrev_b32_e32 v35, 16, v42
	v_pk_mul_f32 v[112:113], v[32:33], v[34:35]
	s_nop 0
	v_fma_f32 v112, 0, v110, v112
	v_fmac_f32_e32 v113, v111, v112
	v_mul_f32_e32 v111, v110, v111
	v_fma_f32 v116, v38, v113, v114
	v_mul_f32_e32 v118, v38, v111
	v_fmac_f32_e32 v115, v39, v116
	v_mul_f32_e32 v114, v39, v118
	ds_write_b64 v61, v[114:115] offset:1536
	v_pk_fma_f32 v[30:31], v[30:31], s[50:51], v[82:83] op_sel_hi:[1,0,0] neg_lo:[1,0,0] neg_hi:[1,0,0]
	v_pk_fma_f32 v[28:29], v[28:29], s[50:51], v[82:83] op_sel_hi:[1,0,0] neg_lo:[1,0,0] neg_hi:[1,0,0]
	v_exp_f32_e32 v30, v30
	v_exp_f32_e32 v31, v31
	v_exp_f32_e32 v28, v28
	v_exp_f32_e32 v29, v29
	v_pk_fma_f32 v[26:27], v[26:27], s[50:51], v[86:87] op_sel_hi:[1,0,0] neg_lo:[1,0,0] neg_hi:[1,0,0]
	v_pk_add_f32 v[30:31], v[30:31], 1.0 op_sel_hi:[1,0]
	v_exp_f32_e32 v26, v26
	v_rcp_f32_e32 v30, v30
	v_rcp_f32_e32 v31, v31
	v_pk_add_f32 v[28:29], v[28:29], 1.0 op_sel_hi:[1,0]
	v_exp_f32_e32 v27, v27
	v_rcp_f32_e32 v28, v28
	v_pk_mul_f32 v[30:31], v[92:93], v[30:31] op_sel_hi:[0,1]
	v_exp_f32_e32 v30, v30
	v_exp_f32_e32 v31, v31
	v_rcp_f32_e32 v29, v29
	v_pk_add_f32 v[26:27], v[26:27], 1.0 op_sel_hi:[1,0]
	v_pk_fma_f32 v[24:25], v[24:25], s[50:51], v[86:87] op_sel_hi:[1,0,0] neg_lo:[1,0,0] neg_hi:[1,0,0]
	v_pk_fma_f32 v[32:33], v[30:31], v[30:31], 1.0 op_sel_hi:[1,1,0] neg_lo:[1,0,0] neg_hi:[1,0,0]
	v_rcp_f32_e32 v26, v26
	v_rcp_f32_e32 v27, v27
	v_sqrt_f32_e32 v32, v32
	v_sqrt_f32_e32 v33, v33
	v_pk_mul_f32 v[28:29], v[92:93], v[28:29] op_sel_hi:[0,1]
	v_exp_f32_e32 v120, v28
	v_exp_f32_e32 v24, v24
	v_exp_f32_e32 v25, v25
	v_exp_f32_e32 v121, v29
	v_pk_mul_f32 v[26:27], v[26:27], v[32:33]
	ds_read_u16 v32, v68 offset:17952
	ds_read_u16 v33, v97 offset:18224
	v_pk_add_f32 v[24:25], v[24:25], 1.0 op_sel_hi:[1,0]
	v_pk_fma_f32 v[28:29], v[120:121], v[120:121], 1.0 op_sel_hi:[1,1,0] neg_lo:[1,0,0] neg_hi:[1,0,0]
	ds_read_u16 v34, v97 offset:17680
	ds_read_u16 v35, v68 offset:17408
	v_rcp_f32_e32 v24, v24
	v_rcp_f32_e32 v25, v25
	v_sqrt_f32_e32 v28, v28
	v_sqrt_f32_e32 v29, v29
	s_waitcnt lgkmcnt(3)
	v_lshlrev_b32_e32 v32, 16, v32
	s_waitcnt lgkmcnt(2)
	v_lshlrev_b32_e32 v33, 16, v33
	v_pk_mul_f32 v[124:125], v[26:27], v[32:33]
	v_pk_mul_f32 v[24:25], v[24:25], v[28:29]
	s_waitcnt lgkmcnt(0)
	v_lshlrev_b32_e32 v26, 16, v35
	v_lshlrev_b32_e32 v27, 16, v34
	v_pk_mul_f32 v[122:123], v[24:25], v[26:27]
	s_nop 0
	v_fma_f32 v122, 0, v120, v122
	v_fmac_f32_e32 v123, v121, v122
	v_mul_f32_e32 v121, v120, v121
	v_fma_f32 v126, v30, v123, v124
	v_mul_f32_e32 v128, v30, v121
	v_fmac_f32_e32 v125, v31, v126
	v_mul_f32_e32 v124, v31, v128
	ds_write_b64 v61, v[124:125] offset:2048
	v_pk_fma_f32 v[22:23], v[22:23], s[50:51], v[82:83] op_sel_hi:[1,0,0] neg_lo:[1,0,0] neg_hi:[1,0,0]
	v_pk_fma_f32 v[20:21], v[20:21], s[50:51], v[82:83] op_sel_hi:[1,0,0] neg_lo:[1,0,0] neg_hi:[1,0,0]
	v_exp_f32_e32 v22, v22
	v_exp_f32_e32 v23, v23
	v_exp_f32_e32 v20, v20
	v_exp_f32_e32 v21, v21
	v_pk_fma_f32 v[18:19], v[18:19], s[50:51], v[86:87] op_sel_hi:[1,0,0] neg_lo:[1,0,0] neg_hi:[1,0,0]
	v_pk_add_f32 v[22:23], v[22:23], 1.0 op_sel_hi:[1,0]
	v_exp_f32_e32 v18, v18
	v_rcp_f32_e32 v22, v22
	v_rcp_f32_e32 v23, v23
	v_pk_add_f32 v[20:21], v[20:21], 1.0 op_sel_hi:[1,0]
	v_exp_f32_e32 v19, v19
	v_rcp_f32_e32 v20, v20
	v_pk_mul_f32 v[22:23], v[92:93], v[22:23] op_sel_hi:[0,1]
	v_exp_f32_e32 v22, v22
	v_exp_f32_e32 v23, v23
	v_rcp_f32_e32 v21, v21
	v_pk_add_f32 v[18:19], v[18:19], 1.0 op_sel_hi:[1,0]
	v_pk_fma_f32 v[16:17], v[16:17], s[50:51], v[86:87] op_sel_hi:[1,0,0] neg_lo:[1,0,0] neg_hi:[1,0,0]
	v_pk_fma_f32 v[24:25], v[22:23], v[22:23], 1.0 op_sel_hi:[1,1,0] neg_lo:[1,0,0] neg_hi:[1,0,0]
	v_rcp_f32_e32 v18, v18
	v_rcp_f32_e32 v19, v19
	v_sqrt_f32_e32 v24, v24
	v_sqrt_f32_e32 v25, v25
	v_pk_mul_f32 v[20:21], v[92:93], v[20:21] op_sel_hi:[0,1]
	v_exp_f32_e32 v130, v20
	v_exp_f32_e32 v16, v16
	v_exp_f32_e32 v17, v17
	v_exp_f32_e32 v131, v21
	v_pk_mul_f32 v[18:19], v[18:19], v[24:25]
	ds_read_u16 v24, v68 offset:22304
	ds_read_u16 v25, v97 offset:22576
	v_pk_add_f32 v[16:17], v[16:17], 1.0 op_sel_hi:[1,0]
	v_pk_fma_f32 v[20:21], v[130:131], v[130:131], 1.0 op_sel_hi:[1,1,0] neg_lo:[1,0,0] neg_hi:[1,0,0]
	ds_read_u16 v26, v97 offset:22032
	ds_read_u16 v27, v68 offset:21760
	v_rcp_f32_e32 v16, v16
	v_rcp_f32_e32 v17, v17
	v_sqrt_f32_e32 v20, v20
	v_sqrt_f32_e32 v21, v21
	s_waitcnt lgkmcnt(3)
	v_lshlrev_b32_e32 v24, 16, v24
	s_waitcnt lgkmcnt(2)
	v_lshlrev_b32_e32 v25, 16, v25
	v_pk_mul_f32 v[134:135], v[18:19], v[24:25]
	v_pk_mul_f32 v[16:17], v[16:17], v[20:21]
	s_waitcnt lgkmcnt(0)
; DI float bf2f(unsigned short b) { return __uint_as_float(((unsigned)b) << 16); }
; DI float ex2(float x) { return __builtin_amdgcn_exp2f(x); }
; DI float rcpf_(float x) { return __builtin_amdgcn_rcpf(x); }
; DI void lru_tile(const Params& p, unsigned char* shm, int c, int nb, const LruPar par) {
;     ...
;         const f32x2 nl2 = {-LOG2E, -LOG2E}, nbr2 = {par.nbr[d], par.nbr[d]}, nbi2 = {par.nbi[d], par.nbi[d]}, cd2 = {par.cdec[d], par.cdec[d]}, one2 = {1.f, 1.f};
;         float hl[8][4], pc[8][4];
; #pragma unroll
;         for (int rt = 0; rt < 8; ++rt) {
;             float av[4], bv[4];
; #pragma unroll
;             for (int jp = 0; jp < 2; ++jp) {
;                 const f32x2 xr = {acc[0][rt][2 * jp], acc[0][rt][2 * jp + 1]}, xi = {acc[1][rt][2 * jp], acc[1][rt][2 * jp + 1]};
;                 f32x2 er = xr * nl2 + nbr2, ei = xi * nl2 + nbi2;
;                 er = (f32x2){ex2(er[0]), ex2(er[1])} + one2; ei = (f32x2){ex2(ei[0]), ex2(ei[1])} + one2;
;                 const f32x2 r = {rcpf_(er[0]), rcpf_(er[1])}, ig = {rcpf_(ei[0]), rcpf_(ei[1])};
;                 const f32x2 la = r * cd2;
;                 const f32x2 a = {ex2(la[0]), ex2(la[1])};
;                 const f32x2 om = one2 - a * a;
;                 const f32x2 sc = {__builtin_amdgcn_sqrtf(om[0]), __builtin_amdgcn_sqrtf(om[1])};
;                 const f32x2 u2 = {bf2f(UB[(rt * 16 + 4 * q + 2 * jp) * LDU + chl]), bf2f(UB[(rt * 16 + 4 * q + 2 * jp + 1) * LDU + chl])};
;                 const f32x2 b2 = sc * ig * u2;
;                 av[2 * jp] = a[0]; av[2 * jp + 1] = a[1]; bv[2 * jp] = b2[0]; bv[2 * jp + 1] = b2[1];
;             }
;             float h = 0.f, P = 1.f;
;             if (d == 0) {
; #pragma unroll
;                 for (int j = 0; j < 4; ++j) { h = fmaf(av[j], h, bv[j]); P *= av[j]; hl[rt][j] = h; pc[rt][j] = P; }
;             } else {
; #pragma unroll
;                 for (int j = 3; j >= 0; --j) { h = fmaf(av[j], h, bv[j]); P *= av[j]; hl[rt][j] = h; pc[rt][j] = P; }
;             }
;             AG[(rt * 4 + q) * 16 + col] = (f32x2){P, h};
;             __builtin_amdgcn_sched_barrier(0);
	v_lshlrev_b32_e32 v18, 16, v27
	v_lshlrev_b32_e32 v19, 16, v26
	v_pk_mul_f32 v[132:133], v[16:17], v[18:19]
	s_nop 0
	v_fma_f32 v132, 0, v130, v132
	v_fmac_f32_e32 v133, v131, v132
	v_mul_f32_e32 v131, v130, v131
	v_fma_f32 v136, v22, v133, v134
	v_mul_f32_e32 v138, v22, v131
	v_fmac_f32_e32 v135, v23, v136
	v_mul_f32_e32 v134, v23, v138
	ds_write_b64 v61, v[134:135] offset:2560
	v_pk_fma_f32 v[14:15], v[14:15], s[50:51], v[82:83] op_sel_hi:[1,0,0] neg_lo:[1,0,0] neg_hi:[1,0,0]
	v_pk_fma_f32 v[12:13], v[12:13], s[50:51], v[82:83] op_sel_hi:[1,0,0] neg_lo:[1,0,0] neg_hi:[1,0,0]
	v_exp_f32_e32 v14, v14
	v_exp_f32_e32 v15, v15
	v_exp_f32_e32 v12, v12
	v_exp_f32_e32 v13, v13
	v_pk_fma_f32 v[10:11], v[10:11], s[50:51], v[86:87] op_sel_hi:[1,0,0] neg_lo:[1,0,0] neg_hi:[1,0,0]
	v_pk_add_f32 v[14:15], v[14:15], 1.0 op_sel_hi:[1,0]
	v_exp_f32_e32 v10, v10
	v_rcp_f32_e32 v14, v14
	v_rcp_f32_e32 v15, v15
	v_pk_add_f32 v[12:13], v[12:13], 1.0 op_sel_hi:[1,0]
	v_exp_f32_e32 v11, v11
	v_rcp_f32_e32 v12, v12
	v_pk_mul_f32 v[14:15], v[92:93], v[14:15] op_sel_hi:[0,1]
	v_exp_f32_e32 v14, v14
	v_exp_f32_e32 v15, v15
	v_rcp_f32_e32 v13, v13
	v_pk_add_f32 v[10:11], v[10:11], 1.0 op_sel_hi:[1,0]
	v_pk_fma_f32 v[8:9], v[8:9], s[50:51], v[86:87] op_sel_hi:[1,0,0] neg_lo:[1,0,0] neg_hi:[1,0,0]
	v_pk_fma_f32 v[16:17], v[14:15], v[14:15], 1.0 op_sel_hi:[1,1,0] neg_lo:[1,0,0] neg_hi:[1,0,0]
	v_rcp_f32_e32 v10, v10
	v_rcp_f32_e32 v11, v11
	v_sqrt_f32_e32 v16, v16
	v_sqrt_f32_e32 v17, v17
	v_pk_mul_f32 v[12:13], v[92:93], v[12:13] op_sel_hi:[0,1]
	v_exp_f32_e32 v140, v12
	v_exp_f32_e32 v8, v8
	v_exp_f32_e32 v9, v9
	v_exp_f32_e32 v141, v13
	v_pk_mul_f32 v[10:11], v[10:11], v[16:17]
	ds_read_u16 v16, v68 offset:26656
	ds_read_u16 v17, v97 offset:26928
	v_pk_add_f32 v[8:9], v[8:9], 1.0 op_sel_hi:[1,0]
	v_pk_fma_f32 v[12:13], v[140:141], v[140:141], 1.0 op_sel_hi:[1,1,0] neg_lo:[1,0,0] neg_hi:[1,0,0]
	ds_read_u16 v18, v97 offset:26384
	ds_read_u16 v19, v68 offset:26112
	v_rcp_f32_e32 v8, v8
	v_rcp_f32_e32 v9, v9
	v_sqrt_f32_e32 v12, v12
	v_sqrt_f32_e32 v13, v13
	s_waitcnt lgkmcnt(3)
	v_lshlrev_b32_e32 v16, 16, v16
	s_waitcnt lgkmcnt(2)
	v_lshlrev_b32_e32 v17, 16, v17
	v_pk_mul_f32 v[144:145], v[10:11], v[16:17]
	v_pk_mul_f32 v[8:9], v[8:9], v[12:13]
	s_waitcnt lgkmcnt(0)
	v_lshlrev_b32_e32 v10, 16, v19
	v_lshlrev_b32_e32 v11, 16, v18
	v_pk_mul_f32 v[142:143], v[8:9], v[10:11]
	s_nop 0
	v_fma_f32 v142, 0, v140, v142
	v_fmac_f32_e32 v143, v141, v142
	v_mul_f32_e32 v141, v140, v141
	v_fma_f32 v146, v14, v143, v144
	v_mul_f32_e32 v148, v14, v141
	v_fmac_f32_e32 v145, v15, v146
	v_mul_f32_e32 v144, v15, v148
	ds_write_b64 v61, v[144:145] offset:3072
	v_pk_fma_f32 v[6:7], v[6:7], s[50:51], v[82:83] op_sel_hi:[1,0,0] neg_lo:[1,0,0] neg_hi:[1,0,0]
	v_pk_fma_f32 v[4:5], v[4:5], s[50:51], v[82:83] op_sel_hi:[1,0,0] neg_lo:[1,0,0] neg_hi:[1,0,0]
	v_exp_f32_e32 v6, v6
	v_exp_f32_e32 v7, v7
	v_exp_f32_e32 v4, v4
	v_exp_f32_e32 v5, v5
	v_pk_fma_f32 v[2:3], v[2:3], s[50:51], v[86:87] op_sel_hi:[1,0,0] neg_lo:[1,0,0] neg_hi:[1,0,0]
	v_pk_add_f32 v[6:7], v[6:7], 1.0 op_sel_hi:[1,0]
	v_exp_f32_e32 v2, v2
	v_rcp_f32_e32 v6, v6
	v_rcp_f32_e32 v7, v7
	v_pk_add_f32 v[4:5], v[4:5], 1.0 op_sel_hi:[1,0]
	v_exp_f32_e32 v3, v3
	v_rcp_f32_e32 v4, v4
	v_pk_mul_f32 v[6:7], v[92:93], v[6:7] op_sel_hi:[0,1]
	v_exp_f32_e32 v6, v6
	v_exp_f32_e32 v7, v7
	v_rcp_f32_e32 v5, v5
	v_pk_add_f32 v[2:3], v[2:3], 1.0 op_sel_hi:[1,0]
	v_pk_fma_f32 v[0:1], v[0:1], s[50:51], v[86:87] op_sel_hi:[1,0,0] neg_lo:[1,0,0] neg_hi:[1,0,0]
	v_pk_fma_f32 v[8:9], v[6:7], v[6:7], 1.0 op_sel_hi:[1,1,0] neg_lo:[1,0,0] neg_hi:[1,0,0]
	v_rcp_f32_e32 v2, v2
	v_rcp_f32_e32 v3, v3
	v_sqrt_f32_e32 v8, v8
	v_sqrt_f32_e32 v9, v9
	v_pk_mul_f32 v[4:5], v[92:93], v[4:5] op_sel_hi:[0,1]
	v_exp_f32_e32 v150, v4
	v_exp_f32_e32 v0, v0
	v_exp_f32_e32 v1, v1
	v_exp_f32_e32 v151, v5
	v_pk_mul_f32 v[2:3], v[2:3], v[8:9]
	ds_read_u16 v8, v68 offset:31008
	ds_read_u16 v9, v97 offset:31280
	v_pk_add_f32 v[0:1], v[0:1], 1.0 op_sel_hi:[1,0]
	v_pk_fma_f32 v[4:5], v[150:151], v[150:151], 1.0 op_sel_hi:[1,1,0] neg_lo:[1,0,0] neg_hi:[1,0,0]
	ds_read_u16 v10, v97 offset:30736
	ds_read_u16 v11, v68 offset:30464
	v_rcp_f32_e32 v0, v0
	v_rcp_f32_e32 v1, v1
	v_sqrt_f32_e32 v4, v4
	v_sqrt_f32_e32 v5, v5
	s_waitcnt lgkmcnt(3)
	v_lshlrev_b32_e32 v8, 16, v8
	s_waitcnt lgkmcnt(2)
	v_lshlrev_b32_e32 v9, 16, v9
	v_pk_mul_f32 v[154:155], v[2:3], v[8:9]
	v_pk_mul_f32 v[0:1], v[0:1], v[4:5]
	s_waitcnt lgkmcnt(0)
	v_lshlrev_b32_e32 v2, 16, v11
	v_lshlrev_b32_e32 v3, 16, v10
	v_pk_mul_f32 v[152:153], v[0:1], v[2:3]
	s_nop 0
	v_fma_f32 v152, 0, v150, v152
	v_fmac_f32_e32 v153, v151, v152
	v_mul_f32_e32 v151, v150, v151
	v_fma_f32 v156, v6, v153, v154
	v_mul_f32_e32 v158, v6, v151
	v_fmac_f32_e32 v155, v7, v156
	v_mul_f32_e32 v154, v7, v158
	ds_write_b64 v61, v[154:155] offset:3584
	s_waitcnt lgkmcnt(0)
; DI void lru_tile(const Params& p, unsigned char* shm, int c, int nb, const LruPar par) {
;     ...
;         asm volatile("s_waitcnt lgkmcnt(0)" ::: "memory");
;         float carry[8], pref[8]; float cin = 0.f, pa = 1.f;
; #pragma unroll
;         for (int gi = 0; gi < 32; ++gi) {
;             const int G = d == 0 ? gi : 31 - gi; const int rt = G >> 2, qq = G & 3;
;             const f32x2 ah = AG[G * 16 + col];
;             if (qq == q) { carry[rt] = cin; pref[rt] = pa; }
;             cin = fmaf(ah[0], cin, ah[1]); pa *= ah[0];
;         }
;         if (q == 0) AGG[((size_t)d * 128 + c) * 2048 + chg] = (f32x2){pa, cin};
	ds_read2_b64 v[0:3], v59 offset1:16
	v_cndmask_b32_e64 v4, v180, 1.0, s[10:11]
	v_cmp_eq_u32_e64 s[4:5], 1, v99
	v_cmp_eq_u32_e64 s[6:7], 2, v99
	v_cmp_eq_u32_e64 s[8:9], 3, v99
	s_waitcnt lgkmcnt(0)
	v_cndmask_b32_e64 v8, v4, v0, s[4:5]
	ds_read2_b64 v[4:7], v59 offset0:32 offset1:48
	v_fma_f32 v119, 0, v0, v1
	v_cndmask_b32_e64 v9, 1.0, v0, s[4:5]
	v_fma_f32 v127, v2, v119, v3
	v_pk_mul_f32 v[0:1], v[0:1], v[2:3]
	s_waitcnt lgkmcnt(0)
	v_fma_f32 v129, v4, v127, v5
	v_cndmask_b32_e64 v2, v8, v0, s[6:7]
	v_pk_mul_f32 v[4:5], v[0:1], v[4:5]
	v_cndmask_b32_e64 v8, v9, v0, s[6:7]
	v_cndmask_b32_e64 v178, v2, v4, s[8:9]
	ds_read2_b64 v[0:3], v59 offset0:64 offset1:80
	v_cndmask_b32_e64 v181, v8, v4, s[8:9]
	v_fma_f32 v137, v6, v129, v7
	v_pk_mul_f32 v[4:5], v[4:5], v[6:7]
	s_waitcnt lgkmcnt(0)
	v_fma_f32 v139, v0, v137, v1
	v_cndmask_b32_e64 v8, v162, v4, s[10:11]
	v_pk_mul_f32 v[0:1], v[4:5], v[0:1]
	ds_read2_b64 v[4:7], v59 offset0:96 offset1:112
	v_cndmask_b32_e64 v8, v8, v0, s[4:5]
	v_fma_f32 v147, v2, v139, v3
	v_pk_mul_f32 v[0:1], v[0:1], v[2:3]
	ds_read_b64 v[162:163], v59 offset:3840
	v_cndmask_b32_e64 v8, v8, v0, s[6:7]
	s_waitcnt lgkmcnt(1)
	v_fma_f32 v149, v4, v147, v5
	v_pk_mul_f32 v[4:5], v[0:1], v[4:5]
	ds_read2_b64 v[0:3], v59 offset0:128 offset1:144
	v_cndmask_b32_e64 v99, v8, v4, s[8:9]
	v_fma_f32 v157, v6, v149, v7
	v_pk_mul_f32 v[4:5], v[4:5], v[6:7]
	s_waitcnt lgkmcnt(0)
	v_fma_f32 v159, v0, v157, v1
	v_cndmask_b32_e64 v8, v91, v4, s[10:11]
	v_pk_mul_f32 v[0:1], v[4:5], v[0:1]
	ds_read2_b64 v[4:7], v59 offset0:160 offset1:176
	v_cndmask_b32_e64 v8, v8, v0, s[4:5]
	v_fma_f32 v183, v2, v159, v3
	v_pk_mul_f32 v[0:1], v[0:1], v[2:3]
	s_waitcnt lgkmcnt(0)
	v_fma_f32 v184, v4, v183, v5
	v_cndmask_b32_e64 v8, v8, v0, s[6:7]
	v_pk_mul_f32 v[4:5], v[0:1], v[4:5]
	ds_read2_b64 v[0:3], v59 offset0:192 offset1:208
	v_cndmask_b32_e64 v107, v8, v4, s[8:9]
	v_fma_f32 v185, v6, v184, v7
	v_pk_mul_f32 v[4:5], v[4:5], v[6:7]
	s_waitcnt lgkmcnt(0)
	v_fma_f32 v186, v0, v185, v1
	v_cndmask_b32_e64 v8, v89, v4, s[10:11]
	v_pk_mul_f32 v[0:1], v[4:5], v[0:1]
	ds_read2_b64 v[4:7], v59 offset0:224 offset1:240
	v_cndmask_b32_e64 v8, v8, v0, s[4:5]
	v_fma_f32 v187, v2, v186, v3
	v_pk_mul_f32 v[0:1], v[0:1], v[2:3]
	v_add_u32_e32 v89, 0x800, v59
	v_cndmask_b32_e64 v8, v8, v0, s[6:7]
	s_waitcnt lgkmcnt(0)
	v_fma_f32 v188, v4, v187, v5
	v_pk_mul_f32 v[4:5], v[0:1], v[4:5]
	ds_read2_b64 v[0:3], v89 offset1:16
	v_cndmask_b32_e64 v109, v8, v4, s[8:9]
	v_fma_f32 v189, v6, v188, v7
	v_pk_mul_f32 v[4:5], v[4:5], v[6:7]
	s_waitcnt lgkmcnt(0)
	v_fma_f32 v190, v0, v189, v1
	v_cndmask_b32_e64 v8, v85, v4, s[10:11]
	v_pk_mul_f32 v[0:1], v[4:5], v[0:1]
	ds_read2_b64 v[4:7], v89 offset0:32 offset1:48
	v_cndmask_b32_e64 v8, v8, v0, s[4:5]
	v_fma_f32 v192, v2, v190, v3
	v_pk_mul_f32 v[0:1], v[0:1], v[2:3]
	s_waitcnt lgkmcnt(0)
	v_fma_f32 v193, v4, v192, v5
	v_cndmask_b32_e64 v8, v8, v0, s[6:7]
	v_pk_mul_f32 v[4:5], v[0:1], v[4:5]
	ds_read2_b64 v[0:3], v89 offset0:64 offset1:80
	v_cndmask_b32_e64 v117, v8, v4, s[8:9]
	v_fma_f32 v194, v6, v193, v7
	v_pk_mul_f32 v[4:5], v[4:5], v[6:7]
	s_waitcnt lgkmcnt(0)
	v_fma_f32 v195, v0, v194, v1
	v_cndmask_b32_e64 v8, v81, v4, s[10:11]
	v_pk_mul_f32 v[0:1], v[4:5], v[0:1]
	ds_read2_b64 v[4:7], v89 offset0:96 offset1:112
	v_cndmask_b32_e64 v8, v8, v0, s[4:5]
	v_fma_f32 v196, v2, v195, v3
	v_pk_mul_f32 v[0:1], v[0:1], v[2:3]
	s_waitcnt lgkmcnt(0)
	v_fma_f32 v197, v4, v196, v5
	v_cndmask_b32_e64 v8, v8, v0, s[6:7]
	v_pk_mul_f32 v[4:5], v[0:1], v[4:5]
	ds_read2_b64 v[0:3], v89 offset0:128 offset1:144
	v_cndmask_b32_e64 v182, v8, v4, s[8:9]
	v_fma_f32 v198, v6, v197, v7
	v_pk_mul_f32 v[4:5], v[4:5], v[6:7]
	s_waitcnt lgkmcnt(0)
	v_fma_f32 v200, v0, v198, v1
	v_cndmask_b32_e64 v8, v79, v4, s[10:11]
	v_pk_mul_f32 v[0:1], v[4:5], v[0:1]
	ds_read2_b64 v[4:7], v89 offset0:160 offset1:176
	v_cndmask_b32_e64 v8, v8, v0, s[4:5]
	v_fma_f32 v201, v2, v200, v3
	v_pk_mul_f32 v[0:1], v[0:1], v[2:3]
	s_waitcnt lgkmcnt(0)
	v_fma_f32 v204, v4, v201, v5
	v_cndmask_b32_e64 v8, v8, v0, s[6:7]
	v_pk_mul_f32 v[4:5], v[0:1], v[4:5]
	ds_read2_b64 v[0:3], v89 offset0:192 offset1:208
	v_cndmask_b32_e64 v191, v8, v4, s[8:9]
	v_fma_f32 v205, v6, v204, v7
	v_pk_mul_f32 v[4:5], v[4:5], v[6:7]
	s_waitcnt lgkmcnt(0)
	v_fma_f32 v206, v0, v205, v1
	v_cndmask_b32_e64 v6, v77, v4, s[10:11]
	v_pk_mul_f32 v[0:1], v[4:5], v[0:1]
	v_fma_f32 v207, v2, v206, v3
	v_cndmask_b32_e64 v4, v6, v0, s[4:5]
	v_pk_mul_f32 v[0:1], v[0:1], v[2:3]
	s_nop 0
	v_cndmask_b32_e64 v77, v4, v0, s[6:7]
	v_pk_mul_f32 v[0:1], v[0:1], v[162:163]
	v_fmac_f32_e32 v163, v162, v207
	v_cndmask_b32_e64 v199, v77, v0, s[8:9]
	s_and_saveexec_b64 s[60:61], s[10:11]
	s_cbranch_execz .LBB0_230
	ds_read_b64 v[2:3], v59 offset:3968
	v_mov_b32_e32 v181, v178
	s_waitcnt lgkmcnt(0)
	v_pk_mul_f32 v[0:1], v[0:1], v[2:3]
	v_fmac_f32_e32 v3, v2, v163
	v_mov_b32_e32 v1, v3
	global_store_dwordx2 v[56:57], v[0:1], off
